# k40 with the modulation GEMM on 96 blocks (one unit each) and the operand build on 160
# baseline (speedup 1.0000x reference)
;     __device__ bool next(int i, Unit& u) const {
;         const long L = (long)i * G + c; if (c < 0 || L >= tot) return false;
;         if (nsplit > 0 && L >= nwg) { const int r = (int)L - nwg, su = r / nsplit, sp = r % nsplit; u.pm = nMfull + su / nN; u.pn = su % nN; u.z = 0; u.k0 = sp * 256; u.nt = 4; u.split = 1; return true; }
;         const int z = (int)(L / nwg); int wgid = (int)(L % nwg);
;         { const int q = nwg / NXCD, r = nwg % NXCD, xcd = wgid % NXCD, off = wgid / NXCD; wgid = (xcd < r ? xcd * (q + 1) : r * (q + 1) + (xcd - r) * q) + off; }
;         const int nig = WGM * nN, gid = wgid / nig, fm = gid * WGM, gsz = (nM - fm) < WGM ? (nM - fm) : WGM;
;         u.pm = fm + ((wgid % nig) % gsz); u.pn = (wgid % nig) / gsz; u.z = z; u.k0 = 0; u.nt = ntK; u.split = 0; return true;
; __global__ void __launch_bounds__(512, 2) hybrid_fwd(Params P) {
;     ...
;         pg8::Gemm g{SC, WMOD, D, D, D, 0, (size_t)6144 * D * 2}; pg8::Order S; S.init(1, 24, DEPTH, G, bid, D / 64);
.LBB0_218:
	s_add_i32 s40, s40, 1
	s_mul_i32 s0, s40, s46
	s_mul_hi_u32 s1, s40, 96
	s_add_i32 s1, s1, s0
	s_mul_i32 s0, s40, 96
	s_add_u32 s0, s0, s29
	s_addc_u32 s1, s1, 0
	v_cmp_gt_i64_e32 vcc, s[0:1], v[138:139]
	v_cmp_lt_i64_e64 s[2:3], s[0:1], v[136:137]
	s_cbranch_vccnz .LBB0_224
	s_mul_i32 s22, s1, 0xaaaaaaab
	s_mul_hi_u32 s23, s0, 0xaaaaaaab
	s_mul_hi_u32 s19, s1, 0xaaaaaaab
	s_add_u32 s22, s22, s23
	s_mul_i32 s17, s0, 0x2aaaaaaa
	s_addc_u32 s19, s19, 0
	s_mul_hi_u32 s16, s0, 0x2aaaaaaa
	s_add_u32 s17, s17, s22
	s_addc_u32 s16, s16, 0
	s_add_u32 s16, s19, s16
	s_addc_u32 s17, 0, 0
	s_mul_i32 s22, s1, 0x2aaaaaaa
	s_mul_hi_u32 s19, s1, 0x2aaaaaaa
	s_add_u32 s16, s22, s16
	s_addc_u32 s17, s19, s17
	s_ashr_i32 s1, s1, 31
	s_mul_i32 s19, s1, 0x2aaaaaaa
	s_mul_hi_u32 s22, s1, 0xaaaaaaab
	s_add_i32 s19, s22, s19
	s_mul_i32 s1, s1, 0xaaaaaaab
	s_add_i32 s19, s19, s1
	s_add_u32 s16, s16, s1
	s_addc_u32 s17, s17, s19
	s_ashr_i64 s[22:23], s[16:17], 2
	s_lshr_b32 s1, s17, 31
	s_add_u32 s50, s22, s1
	s_mul_i32 s1, s50, 24
	s_sub_i32 s0, s0, s1
	s_bfe_i32 s1, s0, 0x80000
	s_bfe_u32 s1, s1, 0x3000c
	s_add_i32 s16, s0, s1
	s_and_b32 s1, s16, 0xf8
	s_sub_i32 s0, s0, s1
	s_bfe_i32 s19, s0, 0x80000
	s_sext_i32_i16 s0, s19
	s_cmp_gt_i32 s0, -1
	s_mov_b64 s[0:1], -1
	s_cbranch_scc0 .LBB0_221
	s_mul_i32 s17, s19, 3
	s_mov_b64 s[0:1], 0
